# A/B: no s_setprio anywhere (flips deleted, no static raise), merged 4-phase K-loops
# baseline (speedup 1.0000x reference)
.LBB0_24:
	v_readlane_b32 s48, v253, 16
	s_mov_b64 s[82:83], 0x60000
	s_movk_i32 s90, 0x104
	v_readfirstlane_b32 s2, v193
	s_nop 1
	s_cmpk_gt_u32 s2, 0xff
	s_cbranch_scc0 .Lprio_skip
